# residual-epilogue x loads of a row group issued together (counted vmcnt) on top of previous edits
# speedup vs baseline: 1.0332x; 1.0121x over previous
.LBB0_264:
	s_ashr_i32 s6, s71, 5
	s_add_i32 s8, s6, 16
	v_readlane_b32 s6, v250, 36
	s_ashr_i32 s9, s71, 4
	v_readlane_b32 s7, v250, 37
	s_and_b64 s[6:7], s[6:7], exec
	s_cselect_b32 s6, s9, s8
	s_mul_hi_i32 s7, s6, 0x9000
	s_mul_i32 s6, s6, 0x9000
	v_readlane_b32 s8, v251, 23
	v_lshl_or_b32 v168, s89, 8, v190
	s_add_u32 s6, s8, s6
	v_readlane_b32 s8, v251, 24
	s_addc_u32 s7, s8, s7
	v_ashrrev_i32_e32 v169, 31, v168
	v_lshl_add_u64 v[166:167], v[168:169], 2, s[6:7]
	global_load_dwordx4 v[134:137], v[166:167], off
	global_load_dwordx4 v[192:195], v[166:167], off offset:576
	v_lshl_add_u32 v170, s71, 8, v188
	v_ashrrev_i32_e32 v171, 31, v170
	s_mov_b64 s[6:7], 0x80000
	s_and_b64 vcc, exec, s[42:43]
	s_mov_b32 s89, s69
	s_mov_b32 s71, s70
	s_mov_b64 s[8:9], s[44:45]
	s_waitcnt vmcnt(0)
	v_pk_mul_f32 v[162:163], v[136:137], 0.5 op_sel_hi:[1,0]
	v_pk_mul_f32 v[164:165], v[134:135], 0.5 op_sel_hi:[1,0]
	global_load_dwordx4 v[134:137], v[166:167], off offset:64
	s_waitcnt vmcnt(0)
	v_pk_mul_f32 v[160:161], v[136:137], 0.5 op_sel_hi:[1,0]
	v_pk_mul_f32 v[142:143], v[134:135], 0.5 op_sel_hi:[1,0]
	global_load_dwordx4 v[134:137], v[166:167], off offset:512
	v_lshlrev_b64 v[166:167], 10, v[170:171]
	v_lshl_add_u64 v[166:167], v[166:167], 0, v[168:169]
	v_lshlrev_b64 v[166:167], 2, v[166:167]
	v_lshl_add_u64 v[196:197], s[38:39], 0, v[166:167]
	s_waitcnt vmcnt(0)
	v_pk_mul_f32 v[140:141], v[136:137], 0.5 op_sel_hi:[1,0]
	v_pk_mul_f32 v[138:139], v[134:135], 0.5 op_sel_hi:[1,0]
	v_pk_mul_f32 v[134:135], v[194:195], 0.5 op_sel_hi:[1,0]
	v_pk_mul_f32 v[136:137], v[192:193], 0.5 op_sel_hi:[1,0]
	global_load_dwordx4 v[200:203], v[196:197], off
	global_load_dwordx4 v[204:207], v[196:197], off offset:64
	global_load_dwordx4 v[208:211], v[196:197], off offset:512
	global_load_dwordx4 v[212:215], v[196:197], off offset:576
	s_waitcnt vmcnt(3)
	v_pk_fma_f32 v[126:127], v[126:127], v[162:163], v[202:203]
	v_pk_fma_f32 v[124:125], v[124:125], v[164:165], v[200:201]
	v_lshl_add_u64 v[192:193], s[96:97], 0, v[166:167]
	global_store_dwordx4 v[192:193], v[124:127], off
	s_waitcnt vmcnt(3)
	v_pk_fma_f32 v[122:123], v[122:123], v[160:161], v[206:207]
	v_pk_fma_f32 v[120:121], v[120:121], v[142:143], v[204:205]
	global_store_dwordx4 v[192:193], v[120:123], off offset:64
	s_waitcnt vmcnt(3)
	v_pk_fma_f32 v[118:119], v[118:119], v[140:141], v[210:211]
	v_pk_fma_f32 v[116:117], v[116:117], v[138:139], v[208:209]
	global_store_dwordx4 v[192:193], v[116:119], off offset:512
	s_waitcnt vmcnt(3)
	v_pk_fma_f32 v[114:115], v[114:115], v[134:135], v[214:215]
	v_pk_fma_f32 v[112:113], v[112:113], v[136:137], v[212:213]
	global_store_dwordx4 v[192:193], v[112:115], off offset:576
	s_nop 1
	v_or_b32_e32 v112, 16, v170
	v_ashrrev_i32_e32 v113, 31, v112
	v_lshlrev_b64 v[112:113], 10, v[112:113]
	v_lshl_add_u64 v[112:113], v[112:113], 0, v[168:169]
	v_lshlrev_b64 v[116:117], 2, v[112:113]
	v_lshl_add_u64 v[118:119], s[38:39], 0, v[116:117]
	global_load_dwordx4 v[200:203], v[118:119], off
	global_load_dwordx4 v[204:207], v[118:119], off offset:64
	global_load_dwordx4 v[208:211], v[118:119], off offset:512
	global_load_dwordx4 v[212:215], v[118:119], off offset:576
	s_waitcnt vmcnt(3)
	v_pk_fma_f32 v[110:111], v[110:111], v[162:163], v[202:203]
	v_pk_fma_f32 v[108:109], v[108:109], v[164:165], v[200:201]
	v_lshl_add_u64 v[112:113], s[96:97], 0, v[116:117]
	global_store_dwordx4 v[112:113], v[108:111], off
	s_waitcnt vmcnt(3)
	v_pk_fma_f32 v[106:107], v[106:107], v[160:161], v[206:207]
	v_pk_fma_f32 v[104:105], v[104:105], v[142:143], v[204:205]
	global_store_dwordx4 v[112:113], v[104:107], off offset:64
	s_waitcnt vmcnt(3)
	v_pk_fma_f32 v[102:103], v[102:103], v[140:141], v[210:211]
	v_pk_fma_f32 v[100:101], v[100:101], v[138:139], v[208:209]
	global_store_dwordx4 v[112:113], v[100:103], off offset:512
	s_waitcnt vmcnt(3)
	v_pk_fma_f32 v[98:99], v[98:99], v[134:135], v[214:215]
	v_pk_fma_f32 v[96:97], v[96:97], v[136:137], v[212:213]
	global_store_dwordx4 v[112:113], v[96:99], off offset:576
	s_nop 1
	v_or_b32_e32 v96, 32, v170
	v_ashrrev_i32_e32 v97, 31, v96
	v_lshlrev_b64 v[96:97], 10, v[96:97]
	v_lshl_add_u64 v[96:97], v[96:97], 0, v[168:169]
	v_lshlrev_b64 v[100:101], 2, v[96:97]
	v_lshl_add_u64 v[102:103], s[38:39], 0, v[100:101]
	global_load_dwordx4 v[200:203], v[102:103], off
	global_load_dwordx4 v[204:207], v[102:103], off offset:64
	global_load_dwordx4 v[208:211], v[102:103], off offset:512
	global_load_dwordx4 v[212:215], v[102:103], off offset:576
	s_waitcnt vmcnt(3)
	v_pk_fma_f32 v[94:95], v[94:95], v[162:163], v[202:203]
	v_pk_fma_f32 v[92:93], v[92:93], v[164:165], v[200:201]
	v_lshl_add_u64 v[96:97], s[96:97], 0, v[100:101]
	global_store_dwordx4 v[96:97], v[92:95], off
	s_waitcnt vmcnt(3)
	v_pk_fma_f32 v[90:91], v[90:91], v[160:161], v[206:207]
	v_pk_fma_f32 v[88:89], v[88:89], v[142:143], v[204:205]
	global_store_dwordx4 v[96:97], v[88:91], off offset:64
	s_waitcnt vmcnt(3)
	v_pk_fma_f32 v[86:87], v[86:87], v[140:141], v[210:211]
	v_pk_fma_f32 v[84:85], v[84:85], v[138:139], v[208:209]
	global_store_dwordx4 v[96:97], v[84:87], off offset:512
	s_waitcnt vmcnt(3)
	v_pk_fma_f32 v[82:83], v[82:83], v[134:135], v[214:215]
	v_pk_fma_f32 v[80:81], v[80:81], v[136:137], v[212:213]
	global_store_dwordx4 v[96:97], v[80:83], off offset:576
	s_nop 1
	v_or_b32_e32 v80, 48, v170
	v_ashrrev_i32_e32 v81, 31, v80
	v_lshlrev_b64 v[80:81], 10, v[80:81]
	v_lshl_add_u64 v[80:81], v[80:81], 0, v[168:169]
	v_lshlrev_b64 v[84:85], 2, v[80:81]
	v_lshl_add_u64 v[86:87], s[38:39], 0, v[84:85]
	global_load_dwordx4 v[200:203], v[86:87], off
	global_load_dwordx4 v[204:207], v[86:87], off offset:64
	global_load_dwordx4 v[208:211], v[86:87], off offset:512
	global_load_dwordx4 v[212:215], v[86:87], off offset:576
	s_waitcnt vmcnt(3)
	v_pk_fma_f32 v[78:79], v[78:79], v[162:163], v[202:203]
	v_pk_fma_f32 v[76:77], v[76:77], v[164:165], v[200:201]
	v_lshl_add_u64 v[80:81], s[96:97], 0, v[84:85]
	global_store_dwordx4 v[80:81], v[76:79], off
	s_waitcnt vmcnt(3)
	v_pk_fma_f32 v[74:75], v[74:75], v[160:161], v[206:207]
	v_pk_fma_f32 v[72:73], v[72:73], v[142:143], v[204:205]
	global_store_dwordx4 v[80:81], v[72:75], off offset:64
	s_waitcnt vmcnt(3)
	v_pk_fma_f32 v[70:71], v[70:71], v[140:141], v[210:211]
	v_pk_fma_f32 v[68:69], v[68:69], v[138:139], v[208:209]
	global_store_dwordx4 v[80:81], v[68:71], off offset:512
	s_waitcnt vmcnt(3)
	v_pk_fma_f32 v[66:67], v[66:67], v[134:135], v[214:215]
	v_pk_fma_f32 v[64:65], v[64:65], v[136:137], v[212:213]
	v_lshl_add_u64 v[68:69], v[166:167], 0, s[6:7]
	global_store_dwordx4 v[80:81], v[64:67], off offset:576
	v_lshl_add_u64 v[70:71], s[38:39], 0, v[68:69]
	global_load_dwordx4 v[64:67], v[70:71], off
	s_mov_b64 s[6:7], 0x90000
	s_waitcnt vmcnt(0)
	v_pk_fma_f32 v[62:63], v[62:63], v[162:163], v[66:67]
	v_pk_fma_f32 v[60:61], v[60:61], v[164:165], v[64:65]
	v_lshl_add_u64 v[64:65], s[96:97], 0, v[68:69]
	global_store_dwordx4 v[64:65], v[60:63], off
	global_load_dwordx4 v[200:203], v[70:71], off offset:64
	global_load_dwordx4 v[204:207], v[70:71], off offset:512
	global_load_dwordx4 v[208:211], v[70:71], off offset:576
	s_waitcnt vmcnt(2)
	v_pk_fma_f32 v[58:59], v[58:59], v[160:161], v[202:203]
	v_pk_fma_f32 v[56:57], v[56:57], v[142:143], v[200:201]
	global_store_dwordx4 v[64:65], v[56:59], off offset:64
	s_waitcnt vmcnt(2)
	v_pk_fma_f32 v[54:55], v[54:55], v[140:141], v[206:207]
	v_pk_fma_f32 v[52:53], v[52:53], v[138:139], v[204:205]
	global_store_dwordx4 v[64:65], v[52:55], off offset:512
	s_waitcnt vmcnt(2)
	v_pk_fma_f32 v[50:51], v[50:51], v[134:135], v[210:211]
	v_pk_fma_f32 v[48:49], v[48:49], v[136:137], v[208:209]
	v_lshl_add_u64 v[52:53], v[166:167], 0, s[6:7]
	global_store_dwordx4 v[64:65], v[48:51], off offset:576
	v_lshl_add_u64 v[54:55], s[38:39], 0, v[52:53]
	global_load_dwordx4 v[48:51], v[54:55], off
	s_mov_b64 s[6:7], 0xa0000
	s_waitcnt vmcnt(0)
	v_pk_fma_f32 v[46:47], v[46:47], v[162:163], v[50:51]
	v_pk_fma_f32 v[44:45], v[44:45], v[164:165], v[48:49]
	v_lshl_add_u64 v[48:49], s[96:97], 0, v[52:53]
	global_store_dwordx4 v[48:49], v[44:47], off
	global_load_dwordx4 v[200:203], v[54:55], off offset:64
	global_load_dwordx4 v[204:207], v[54:55], off offset:512
	global_load_dwordx4 v[208:211], v[54:55], off offset:576
	s_waitcnt vmcnt(2)
	v_pk_fma_f32 v[42:43], v[42:43], v[160:161], v[202:203]
	v_pk_fma_f32 v[40:41], v[40:41], v[142:143], v[200:201]
	global_store_dwordx4 v[48:49], v[40:43], off offset:64
	s_waitcnt vmcnt(2)
	v_pk_fma_f32 v[38:39], v[38:39], v[140:141], v[206:207]
	v_pk_fma_f32 v[36:37], v[36:37], v[138:139], v[204:205]
	global_store_dwordx4 v[48:49], v[36:39], off offset:512
	s_waitcnt vmcnt(2)
	v_pk_fma_f32 v[34:35], v[34:35], v[134:135], v[210:211]
	v_pk_fma_f32 v[32:33], v[32:33], v[136:137], v[208:209]
	v_lshl_add_u64 v[36:37], v[166:167], 0, s[6:7]
	global_store_dwordx4 v[48:49], v[32:35], off offset:576
	v_lshl_add_u64 v[38:39], s[38:39], 0, v[36:37]
	global_load_dwordx4 v[32:35], v[38:39], off
	s_mov_b64 s[6:7], 0xb0000
	s_waitcnt vmcnt(0)
	v_pk_fma_f32 v[30:31], v[30:31], v[162:163], v[34:35]
	v_pk_fma_f32 v[28:29], v[28:29], v[164:165], v[32:33]
	v_lshl_add_u64 v[32:33], s[96:97], 0, v[36:37]
	global_store_dwordx4 v[32:33], v[28:31], off
	global_load_dwordx4 v[200:203], v[38:39], off offset:64
	global_load_dwordx4 v[204:207], v[38:39], off offset:512
	global_load_dwordx4 v[208:211], v[38:39], off offset:576
	s_waitcnt vmcnt(2)
	v_pk_fma_f32 v[26:27], v[26:27], v[160:161], v[202:203]
	v_pk_fma_f32 v[24:25], v[24:25], v[142:143], v[200:201]
	global_store_dwordx4 v[32:33], v[24:27], off offset:64
	s_waitcnt vmcnt(2)
	v_pk_fma_f32 v[22:23], v[22:23], v[140:141], v[206:207]
	v_pk_fma_f32 v[20:21], v[20:21], v[138:139], v[204:205]
	global_store_dwordx4 v[32:33], v[20:23], off offset:512
	s_waitcnt vmcnt(2)
	v_pk_fma_f32 v[18:19], v[18:19], v[134:135], v[210:211]
	v_pk_fma_f32 v[16:17], v[16:17], v[136:137], v[208:209]
	v_lshl_add_u64 v[20:21], v[166:167], 0, s[6:7]
	global_store_dwordx4 v[32:33], v[16:19], off offset:576
	v_lshl_add_u64 v[22:23], s[38:39], 0, v[20:21]
	global_load_dwordx4 v[16:19], v[22:23], off
	s_mov_b64 s[6:7], s[46:47]
	s_waitcnt vmcnt(0)
	v_pk_fma_f32 v[14:15], v[14:15], v[162:163], v[18:19]
	v_pk_fma_f32 v[12:13], v[12:13], v[164:165], v[16:17]
	v_lshl_add_u64 v[16:17], s[96:97], 0, v[20:21]
	global_store_dwordx4 v[16:17], v[12:15], off
	global_load_dwordx4 v[200:203], v[22:23], off offset:64
	global_load_dwordx4 v[204:207], v[22:23], off offset:512
	global_load_dwordx4 v[208:211], v[22:23], off offset:576
	s_waitcnt vmcnt(2)
	v_pk_fma_f32 v[10:11], v[10:11], v[160:161], v[202:203]
	v_pk_fma_f32 v[8:9], v[8:9], v[142:143], v[200:201]
	global_store_dwordx4 v[16:17], v[8:11], off offset:64
	s_waitcnt vmcnt(2)
	v_pk_fma_f32 v[6:7], v[6:7], v[140:141], v[206:207]
	v_pk_fma_f32 v[4:5], v[4:5], v[138:139], v[204:205]
	global_store_dwordx4 v[16:17], v[4:7], off offset:512
	s_waitcnt vmcnt(2)
	v_pk_fma_f32 v[2:3], v[2:3], v[134:135], v[210:211]
	v_pk_fma_f32 v[0:1], v[0:1], v[136:137], v[208:209]
	global_store_dwordx4 v[16:17], v[0:3], off offset:576
	s_cbranch_vccnz .LBB0_278

.LBB0_922:
	s_ashr_i32 s6, s69, 5
	s_add_i32 s8, s6, 16
	v_readlane_b32 s6, v250, 36
	s_ashr_i32 s9, s69, 4
	v_readlane_b32 s7, v250, 37
	s_and_b64 s[6:7], s[6:7], exec
	s_cselect_b32 s6, s9, s8
	v_lshl_add_u32 v170, s69, 8, v188
	v_lshl_or_b32 v80, s70, 8, v190
	s_mul_hi_i32 s7, s6, 0x9000
	s_mul_i32 s6, s6, 0x9000
	v_readlane_b32 s8, v251, 46
	v_ashrrev_i32_e32 v171, 31, v170
	s_add_u32 s6, s8, s6
	v_readlane_b32 s8, v251, 47
	v_ashrrev_i32_e32 v81, 31, v80
	v_lshlrev_b64 v[166:167], 12, v[170:171]
	s_addc_u32 s7, s8, s7
	v_lshlrev_b64 v[168:169], 2, v[80:81]
	v_lshl_add_u64 v[166:167], s[96:97], 0, v[166:167]
	v_lshl_add_u64 v[80:81], s[6:7], 0, v[168:169]
	v_lshl_add_u64 v[166:167], v[166:167], 0, v[168:169]
	global_load_dwordx4 v[140:143], v[80:81], off
	global_load_dwordx4 v[136:139], v[80:81], off offset:64
	global_load_dwordx4 v[132:135], v[80:81], off offset:512
	s_nop 0
	global_load_dwordx4 v[80:83], v[80:81], off offset:576
	s_mov_b64 s[6:7], 0x80000
	global_load_dwordx4 v[192:195], v[166:167], off
	s_mov_b32 s70, s61
	s_mov_b32 s69, s68
	s_mov_b64 s[8:9], s[44:45]
	s_waitcnt vmcnt(0)
	v_pk_fma_f32 v[130:131], v[130:131], v[142:143], v[194:195]
	v_pk_fma_f32 v[128:129], v[128:129], v[140:141], v[192:193]
	global_store_dwordx4 v[166:167], v[128:131], off
	global_load_dwordx4 v[200:203], v[166:167], off offset:64
	global_load_dwordx4 v[204:207], v[166:167], off offset:512
	global_load_dwordx4 v[208:211], v[166:167], off offset:576
	s_waitcnt vmcnt(2)
	v_pk_fma_f32 v[126:127], v[126:127], v[138:139], v[202:203]
	v_pk_fma_f32 v[124:125], v[124:125], v[136:137], v[200:201]
	global_store_dwordx4 v[166:167], v[124:127], off offset:64
	s_waitcnt vmcnt(2)
	v_pk_fma_f32 v[122:123], v[122:123], v[134:135], v[206:207]
	v_pk_fma_f32 v[120:121], v[120:121], v[132:133], v[204:205]
	global_store_dwordx4 v[166:167], v[120:123], off offset:512
	s_waitcnt vmcnt(2)
	v_pk_fma_f32 v[118:119], v[118:119], v[82:83], v[210:211]
	v_pk_fma_f32 v[116:117], v[116:117], v[80:81], v[208:209]
	global_store_dwordx4 v[166:167], v[116:119], off offset:576
	s_nop 1
	v_or_b32_e32 v116, 16, v170
	v_ashrrev_i32_e32 v117, 31, v116
	v_lshlrev_b64 v[116:117], 12, v[116:117]
	v_lshl_add_u64 v[116:117], s[96:97], 0, v[116:117]
	v_lshl_add_u64 v[120:121], v[116:117], 0, v[168:169]
	global_load_dwordx4 v[200:203], v[120:121], off
	global_load_dwordx4 v[204:207], v[120:121], off offset:64
	global_load_dwordx4 v[208:211], v[120:121], off offset:512
	global_load_dwordx4 v[212:215], v[120:121], off offset:576
	s_waitcnt vmcnt(3)
	v_pk_fma_f32 v[114:115], v[114:115], v[142:143], v[202:203]
	v_pk_fma_f32 v[112:113], v[112:113], v[140:141], v[200:201]
	global_store_dwordx4 v[120:121], v[112:115], off
	s_waitcnt vmcnt(3)
	v_pk_fma_f32 v[110:111], v[110:111], v[138:139], v[206:207]
	v_pk_fma_f32 v[108:109], v[108:109], v[136:137], v[204:205]
	global_store_dwordx4 v[120:121], v[108:111], off offset:64
	s_waitcnt vmcnt(3)
	v_pk_fma_f32 v[106:107], v[106:107], v[134:135], v[210:211]
	v_pk_fma_f32 v[104:105], v[104:105], v[132:133], v[208:209]
	global_store_dwordx4 v[120:121], v[104:107], off offset:512
	s_waitcnt vmcnt(3)
	v_pk_fma_f32 v[102:103], v[102:103], v[82:83], v[214:215]
	v_pk_fma_f32 v[100:101], v[100:101], v[80:81], v[212:213]
	global_store_dwordx4 v[120:121], v[100:103], off offset:576
	s_nop 1
	v_or_b32_e32 v100, 32, v170
	v_ashrrev_i32_e32 v101, 31, v100
	v_lshlrev_b64 v[100:101], 12, v[100:101]
	v_lshl_add_u64 v[100:101], s[96:97], 0, v[100:101]
	v_lshl_add_u64 v[104:105], v[100:101], 0, v[168:169]
	global_load_dwordx4 v[200:203], v[104:105], off
	global_load_dwordx4 v[204:207], v[104:105], off offset:64
	global_load_dwordx4 v[208:211], v[104:105], off offset:512
	global_load_dwordx4 v[212:215], v[104:105], off offset:576
	s_waitcnt vmcnt(3)
	v_pk_fma_f32 v[98:99], v[98:99], v[142:143], v[202:203]
	v_pk_fma_f32 v[96:97], v[96:97], v[140:141], v[200:201]
	global_store_dwordx4 v[104:105], v[96:99], off
	s_waitcnt vmcnt(3)
	v_pk_fma_f32 v[94:95], v[94:95], v[138:139], v[206:207]
	v_pk_fma_f32 v[92:93], v[92:93], v[136:137], v[204:205]
	global_store_dwordx4 v[104:105], v[92:95], off offset:64
	s_waitcnt vmcnt(3)
	v_pk_fma_f32 v[90:91], v[90:91], v[134:135], v[210:211]
	v_pk_fma_f32 v[88:89], v[88:89], v[132:133], v[208:209]
	global_store_dwordx4 v[104:105], v[88:91], off offset:512
	s_waitcnt vmcnt(3)
	v_pk_fma_f32 v[86:87], v[86:87], v[82:83], v[214:215]
	v_pk_fma_f32 v[84:85], v[84:85], v[80:81], v[212:213]
	global_store_dwordx4 v[104:105], v[84:87], off offset:576
	s_nop 1
	v_or_b32_e32 v84, 48, v170
	v_ashrrev_i32_e32 v85, 31, v84
	v_lshlrev_b64 v[84:85], 12, v[84:85]
	v_lshl_add_u64 v[84:85], s[96:97], 0, v[84:85]
	v_lshl_add_u64 v[88:89], v[84:85], 0, v[168:169]
	global_load_dwordx4 v[200:203], v[88:89], off
	global_load_dwordx4 v[204:207], v[88:89], off offset:64
	global_load_dwordx4 v[208:211], v[88:89], off offset:512
	s_waitcnt vmcnt(2)
	v_pk_fma_f32 v[78:79], v[78:79], v[142:143], v[202:203]
	v_pk_fma_f32 v[76:77], v[76:77], v[140:141], v[200:201]
	global_store_dwordx4 v[88:89], v[76:79], off
	s_waitcnt vmcnt(2)
	v_pk_fma_f32 v[74:75], v[74:75], v[138:139], v[206:207]
	v_pk_fma_f32 v[72:73], v[72:73], v[136:137], v[204:205]
	global_store_dwordx4 v[88:89], v[72:75], off offset:64
	s_waitcnt vmcnt(2)
	v_pk_fma_f32 v[70:71], v[70:71], v[134:135], v[210:211]
	v_pk_fma_f32 v[68:69], v[68:69], v[132:133], v[208:209]
	global_store_dwordx4 v[88:89], v[68:71], off offset:512
	global_load_dwordx4 v[68:71], v[88:89], off offset:576
	s_waitcnt vmcnt(0)
	v_pk_fma_f32 v[64:65], v[64:65], v[80:81], v[68:69]
	v_lshl_add_u64 v[68:69], v[166:167], 0, s[6:7]
	s_mov_b32 s6, 0x80000
	v_pk_fma_f32 v[66:67], v[66:67], v[82:83], v[70:71]
	v_add_co_u32_e32 v70, vcc, s6, v166
	global_store_dwordx4 v[88:89], v[64:67], off offset:576
	s_nop 0
	v_addc_co_u32_e32 v71, vcc, 0, v167, vcc
	global_load_dwordx4 v[64:67], v[70:71], off
	s_mov_b64 s[6:7], 0x90000
	s_waitcnt vmcnt(0)
	v_pk_fma_f32 v[62:63], v[62:63], v[142:143], v[66:67]
	v_pk_fma_f32 v[60:61], v[60:61], v[140:141], v[64:65]
	global_store_dwordx4 v[70:71], v[60:63], off
	global_load_dwordx4 v[200:203], v[68:69], off offset:64
	global_load_dwordx4 v[204:207], v[68:69], off offset:512
	s_waitcnt vmcnt(1)
	v_pk_fma_f32 v[58:59], v[58:59], v[138:139], v[202:203]
	v_pk_fma_f32 v[56:57], v[56:57], v[136:137], v[200:201]
	global_store_dwordx4 v[68:69], v[56:59], off offset:64
	s_waitcnt vmcnt(1)
	v_pk_fma_f32 v[54:55], v[54:55], v[134:135], v[206:207]
	v_pk_fma_f32 v[52:53], v[52:53], v[132:133], v[204:205]
	global_store_dwordx4 v[68:69], v[52:55], off offset:512
	global_load_dwordx4 v[52:55], v[68:69], off offset:576
	s_waitcnt vmcnt(0)
	v_pk_fma_f32 v[48:49], v[48:49], v[80:81], v[52:53]
	v_lshl_add_u64 v[52:53], v[166:167], 0, s[6:7]
	s_mov_b32 s6, 0x90000
	v_pk_fma_f32 v[50:51], v[50:51], v[82:83], v[54:55]
	v_add_co_u32_e32 v54, vcc, s6, v166
	global_store_dwordx4 v[68:69], v[48:51], off offset:576
	s_nop 0
	v_addc_co_u32_e32 v55, vcc, 0, v167, vcc
	global_load_dwordx4 v[48:51], v[54:55], off
	s_mov_b64 s[6:7], 0xa0000
	s_waitcnt vmcnt(0)
	v_pk_fma_f32 v[46:47], v[46:47], v[142:143], v[50:51]
	v_pk_fma_f32 v[44:45], v[44:45], v[140:141], v[48:49]
	global_store_dwordx4 v[54:55], v[44:47], off
	global_load_dwordx4 v[200:203], v[52:53], off offset:64
	global_load_dwordx4 v[204:207], v[52:53], off offset:512
	global_load_dwordx4 v[208:211], v[52:53], off offset:576
	s_waitcnt vmcnt(2)
	v_pk_fma_f32 v[42:43], v[42:43], v[138:139], v[202:203]
	v_pk_fma_f32 v[40:41], v[40:41], v[136:137], v[200:201]
	global_store_dwordx4 v[52:53], v[40:43], off offset:64
	s_waitcnt vmcnt(2)
	v_pk_fma_f32 v[38:39], v[38:39], v[134:135], v[206:207]
	v_pk_fma_f32 v[36:37], v[36:37], v[132:133], v[204:205]
	global_store_dwordx4 v[52:53], v[36:39], off offset:512
	s_waitcnt vmcnt(2)
	v_pk_fma_f32 v[34:35], v[34:35], v[82:83], v[210:211]
	v_pk_fma_f32 v[32:33], v[32:33], v[80:81], v[208:209]
	global_store_dwordx4 v[52:53], v[32:35], off offset:576
	s_nop 1
	v_lshl_add_u64 v[32:33], v[166:167], 0, s[6:7]
	s_mov_b32 s6, 0xa0000
	v_add_co_u32_e32 v38, vcc, s6, v166
	s_mov_b64 s[6:7], 0xb0000
	s_nop 0
	v_addc_co_u32_e32 v39, vcc, 0, v167, vcc
	global_load_dwordx4 v[34:37], v[38:39], off
	s_waitcnt vmcnt(0)
	v_pk_fma_f32 v[30:31], v[30:31], v[142:143], v[36:37]
	v_pk_fma_f32 v[28:29], v[28:29], v[140:141], v[34:35]
	global_store_dwordx4 v[38:39], v[28:31], off
	global_load_dwordx4 v[200:203], v[32:33], off offset:64
	global_load_dwordx4 v[204:207], v[32:33], off offset:512
	global_load_dwordx4 v[208:211], v[32:33], off offset:576
	s_waitcnt vmcnt(2)
	v_pk_fma_f32 v[26:27], v[26:27], v[138:139], v[202:203]
	v_pk_fma_f32 v[24:25], v[24:25], v[136:137], v[200:201]
	global_store_dwordx4 v[32:33], v[24:27], off offset:64
	s_waitcnt vmcnt(2)
	v_pk_fma_f32 v[22:23], v[22:23], v[134:135], v[206:207]
	v_pk_fma_f32 v[20:21], v[20:21], v[132:133], v[204:205]
	global_store_dwordx4 v[32:33], v[20:23], off offset:512
	s_waitcnt vmcnt(2)
	v_pk_fma_f32 v[18:19], v[18:19], v[82:83], v[210:211]
	v_pk_fma_f32 v[16:17], v[16:17], v[80:81], v[208:209]
	global_store_dwordx4 v[32:33], v[16:19], off offset:576
	s_nop 1
	v_lshl_add_u64 v[16:17], v[166:167], 0, s[6:7]
	s_mov_b32 s6, 0xb0000
	v_add_co_u32_e32 v22, vcc, s6, v166
	s_mov_b64 s[6:7], s[46:47]
	s_nop 0
	v_addc_co_u32_e32 v23, vcc, 0, v167, vcc
	global_load_dwordx4 v[18:21], v[22:23], off
	s_and_b64 vcc, exec, s[42:43]
	s_waitcnt vmcnt(0)
	v_pk_fma_f32 v[14:15], v[14:15], v[142:143], v[20:21]
	v_pk_fma_f32 v[12:13], v[12:13], v[140:141], v[18:19]
	global_store_dwordx4 v[22:23], v[12:15], off
	global_load_dwordx4 v[200:203], v[16:17], off offset:64
	global_load_dwordx4 v[204:207], v[16:17], off offset:512
	global_load_dwordx4 v[208:211], v[16:17], off offset:576
	s_waitcnt vmcnt(2)
	v_pk_fma_f32 v[10:11], v[10:11], v[138:139], v[202:203]
	v_pk_fma_f32 v[8:9], v[8:9], v[136:137], v[200:201]
	global_store_dwordx4 v[16:17], v[8:11], off offset:64
	s_waitcnt vmcnt(2)
	v_pk_fma_f32 v[6:7], v[6:7], v[134:135], v[206:207]
	v_pk_fma_f32 v[4:5], v[4:5], v[132:133], v[204:205]
	global_store_dwordx4 v[16:17], v[4:7], off offset:512
	s_waitcnt vmcnt(2)
	v_pk_fma_f32 v[2:3], v[2:3], v[82:83], v[210:211]
	v_pk_fma_f32 v[0:1], v[0:1], v[80:81], v[208:209]
	global_store_dwordx4 v[16:17], v[0:3], off offset:576
	s_cbranch_vccnz .LBB0_936

.LBB0_1119:
	s_ashr_i32 s6, s69, 5
	s_add_i32 s8, s6, 16
	v_readlane_b32 s6, v250, 36
	s_ashr_i32 s9, s69, 4
	v_readlane_b32 s7, v250, 37
	s_and_b64 s[6:7], s[6:7], exec
	s_cselect_b32 s6, s9, s8
	v_lshl_or_b32 v134, s70, 8, v190
	s_mul_hi_i32 s7, s6, 0x9000
	s_mul_i32 s6, s6, 0x9000
	v_readlane_b32 s8, v251, 52
	s_add_u32 s6, s8, s6
	v_readlane_b32 s8, v251, 53
	v_ashrrev_i32_e32 v135, 31, v134
	s_addc_u32 s7, s8, s7
	v_lshlrev_b64 v[168:169], 2, v[134:135]
	v_lshl_add_u64 v[166:167], s[6:7], 0, v[168:169]
	global_load_dwordx4 v[134:137], v[166:167], off
	v_lshl_add_u32 v170, s69, 8, v188
	v_ashrrev_i32_e32 v171, 31, v170
	s_mov_b64 s[6:7], 0x80000
	s_mov_b32 s70, s61
	s_mov_b32 s69, s68
	s_mov_b64 s[8:9], s[40:41]
	s_waitcnt vmcnt(0)
	v_pk_mul_f32 v[162:163], v[136:137], 0.5 op_sel_hi:[1,0]
	v_pk_mul_f32 v[164:165], v[134:135], 0.5 op_sel_hi:[1,0]
	global_load_dwordx4 v[134:137], v[166:167], off offset:64
	s_waitcnt vmcnt(0)
	v_pk_mul_f32 v[142:143], v[136:137], 0.5 op_sel_hi:[1,0]
	v_pk_mul_f32 v[160:161], v[134:135], 0.5 op_sel_hi:[1,0]
	global_load_dwordx4 v[134:137], v[166:167], off offset:512
	s_waitcnt vmcnt(0)
	v_pk_mul_f32 v[138:139], v[136:137], 0.5 op_sel_hi:[1,0]
	v_pk_mul_f32 v[140:141], v[134:135], 0.5 op_sel_hi:[1,0]
	global_load_dwordx4 v[134:137], v[166:167], off offset:576
	v_lshlrev_b64 v[166:167], 12, v[170:171]
	v_lshl_add_u64 v[166:167], s[96:97], 0, v[166:167]
	v_lshl_add_u64 v[166:167], v[166:167], 0, v[168:169]
	global_load_dwordx4 v[192:195], v[166:167], off
	s_waitcnt vmcnt(0)
	v_pk_mul_f32 v[136:137], v[136:137], 0.5 op_sel_hi:[1,0]
	v_pk_mul_f32 v[134:135], v[134:135], 0.5 op_sel_hi:[1,0]
	v_pk_fma_f32 v[126:127], v[126:127], v[162:163], v[194:195]
	v_pk_fma_f32 v[124:125], v[124:125], v[164:165], v[192:193]
	global_store_dwordx4 v[166:167], v[124:127], off
	global_load_dwordx4 v[200:203], v[166:167], off offset:64
	global_load_dwordx4 v[204:207], v[166:167], off offset:512
	global_load_dwordx4 v[208:211], v[166:167], off offset:576
	s_waitcnt vmcnt(2)
	v_pk_fma_f32 v[122:123], v[122:123], v[142:143], v[202:203]
	v_pk_fma_f32 v[120:121], v[120:121], v[160:161], v[200:201]
	global_store_dwordx4 v[166:167], v[120:123], off offset:64
	s_waitcnt vmcnt(2)
	v_pk_fma_f32 v[118:119], v[118:119], v[138:139], v[206:207]
	v_pk_fma_f32 v[116:117], v[116:117], v[140:141], v[204:205]
	global_store_dwordx4 v[166:167], v[116:119], off offset:512
	s_waitcnt vmcnt(2)
	v_pk_fma_f32 v[114:115], v[114:115], v[136:137], v[210:211]
	v_pk_fma_f32 v[112:113], v[112:113], v[134:135], v[208:209]
	global_store_dwordx4 v[166:167], v[112:115], off offset:576
	s_nop 1
	v_or_b32_e32 v112, 16, v170
	v_ashrrev_i32_e32 v113, 31, v112
	v_lshlrev_b64 v[112:113], 12, v[112:113]
	v_lshl_add_u64 v[112:113], s[96:97], 0, v[112:113]
	v_lshl_add_u64 v[116:117], v[112:113], 0, v[168:169]
	global_load_dwordx4 v[200:203], v[116:117], off
	global_load_dwordx4 v[204:207], v[116:117], off offset:64
	global_load_dwordx4 v[208:211], v[116:117], off offset:512
	global_load_dwordx4 v[212:215], v[116:117], off offset:576
	s_waitcnt vmcnt(3)
	v_pk_fma_f32 v[110:111], v[110:111], v[162:163], v[202:203]
	v_pk_fma_f32 v[108:109], v[108:109], v[164:165], v[200:201]
	global_store_dwordx4 v[116:117], v[108:111], off
	s_waitcnt vmcnt(3)
	v_pk_fma_f32 v[106:107], v[106:107], v[142:143], v[206:207]
	v_pk_fma_f32 v[104:105], v[104:105], v[160:161], v[204:205]
	global_store_dwordx4 v[116:117], v[104:107], off offset:64
	s_waitcnt vmcnt(3)
	v_pk_fma_f32 v[102:103], v[102:103], v[138:139], v[210:211]
	v_pk_fma_f32 v[100:101], v[100:101], v[140:141], v[208:209]
	global_store_dwordx4 v[116:117], v[100:103], off offset:512
	s_waitcnt vmcnt(3)
	v_pk_fma_f32 v[98:99], v[98:99], v[136:137], v[214:215]
	v_pk_fma_f32 v[96:97], v[96:97], v[134:135], v[212:213]
	global_store_dwordx4 v[116:117], v[96:99], off offset:576
	s_nop 1
	v_or_b32_e32 v96, 32, v170
	v_ashrrev_i32_e32 v97, 31, v96
	v_lshlrev_b64 v[96:97], 12, v[96:97]
	v_lshl_add_u64 v[96:97], s[96:97], 0, v[96:97]
	v_lshl_add_u64 v[100:101], v[96:97], 0, v[168:169]
	global_load_dwordx4 v[200:203], v[100:101], off
	global_load_dwordx4 v[204:207], v[100:101], off offset:64
	global_load_dwordx4 v[208:211], v[100:101], off offset:512
	global_load_dwordx4 v[212:215], v[100:101], off offset:576
	s_waitcnt vmcnt(3)
	v_pk_fma_f32 v[94:95], v[94:95], v[162:163], v[202:203]
	v_pk_fma_f32 v[92:93], v[92:93], v[164:165], v[200:201]
	global_store_dwordx4 v[100:101], v[92:95], off
	s_waitcnt vmcnt(3)
	v_pk_fma_f32 v[90:91], v[90:91], v[142:143], v[206:207]
	v_pk_fma_f32 v[88:89], v[88:89], v[160:161], v[204:205]
	global_store_dwordx4 v[100:101], v[88:91], off offset:64
	s_waitcnt vmcnt(3)
	v_pk_fma_f32 v[86:87], v[86:87], v[138:139], v[210:211]
	v_pk_fma_f32 v[84:85], v[84:85], v[140:141], v[208:209]
	global_store_dwordx4 v[100:101], v[84:87], off offset:512
	s_waitcnt vmcnt(3)
	v_pk_fma_f32 v[82:83], v[82:83], v[136:137], v[214:215]
	v_pk_fma_f32 v[80:81], v[80:81], v[134:135], v[212:213]
	global_store_dwordx4 v[100:101], v[80:83], off offset:576
	s_nop 1
	v_or_b32_e32 v80, 48, v170
	v_ashrrev_i32_e32 v81, 31, v80
	v_lshlrev_b64 v[80:81], 12, v[80:81]
	v_lshl_add_u64 v[80:81], s[96:97], 0, v[80:81]
	v_lshl_add_u64 v[84:85], v[80:81], 0, v[168:169]
	global_load_dwordx4 v[200:203], v[84:85], off
	global_load_dwordx4 v[204:207], v[84:85], off offset:64
	global_load_dwordx4 v[208:211], v[84:85], off offset:512
	s_waitcnt vmcnt(2)
	v_pk_fma_f32 v[78:79], v[78:79], v[162:163], v[202:203]
	v_pk_fma_f32 v[76:77], v[76:77], v[164:165], v[200:201]
	global_store_dwordx4 v[84:85], v[76:79], off
	s_waitcnt vmcnt(2)
	v_pk_fma_f32 v[74:75], v[74:75], v[142:143], v[206:207]
	v_pk_fma_f32 v[72:73], v[72:73], v[160:161], v[204:205]
	global_store_dwordx4 v[84:85], v[72:75], off offset:64
	s_waitcnt vmcnt(2)
	v_pk_fma_f32 v[70:71], v[70:71], v[138:139], v[210:211]
	v_pk_fma_f32 v[68:69], v[68:69], v[140:141], v[208:209]
	global_store_dwordx4 v[84:85], v[68:71], off offset:512
	global_load_dwordx4 v[68:71], v[84:85], off offset:576
	s_waitcnt vmcnt(0)
	v_pk_fma_f32 v[64:65], v[64:65], v[134:135], v[68:69]
	v_lshl_add_u64 v[68:69], v[166:167], 0, s[6:7]
	s_mov_b32 s6, 0x80000
	v_pk_fma_f32 v[66:67], v[66:67], v[136:137], v[70:71]
	v_add_co_u32_e32 v70, vcc, s6, v166
	global_store_dwordx4 v[84:85], v[64:67], off offset:576
	s_nop 0
	v_addc_co_u32_e32 v71, vcc, 0, v167, vcc
	global_load_dwordx4 v[64:67], v[70:71], off
	s_mov_b64 s[6:7], 0x90000
	s_waitcnt vmcnt(0)
	v_pk_fma_f32 v[62:63], v[62:63], v[162:163], v[66:67]
	v_pk_fma_f32 v[60:61], v[60:61], v[164:165], v[64:65]
	global_store_dwordx4 v[70:71], v[60:63], off
	global_load_dwordx4 v[200:203], v[68:69], off offset:64
	global_load_dwordx4 v[204:207], v[68:69], off offset:512
	s_waitcnt vmcnt(1)
	v_pk_fma_f32 v[58:59], v[58:59], v[142:143], v[202:203]
	v_pk_fma_f32 v[56:57], v[56:57], v[160:161], v[200:201]
	global_store_dwordx4 v[68:69], v[56:59], off offset:64
	s_waitcnt vmcnt(1)
	v_pk_fma_f32 v[54:55], v[54:55], v[138:139], v[206:207]
	v_pk_fma_f32 v[52:53], v[52:53], v[140:141], v[204:205]
	global_store_dwordx4 v[68:69], v[52:55], off offset:512
	global_load_dwordx4 v[52:55], v[68:69], off offset:576
	s_waitcnt vmcnt(0)
	v_pk_fma_f32 v[48:49], v[48:49], v[134:135], v[52:53]
	v_lshl_add_u64 v[52:53], v[166:167], 0, s[6:7]
	s_mov_b32 s6, 0x90000
	v_pk_fma_f32 v[50:51], v[50:51], v[136:137], v[54:55]
	v_add_co_u32_e32 v54, vcc, s6, v166
	global_store_dwordx4 v[68:69], v[48:51], off offset:576
	s_nop 0
	v_addc_co_u32_e32 v55, vcc, 0, v167, vcc
	global_load_dwordx4 v[48:51], v[54:55], off
	s_mov_b64 s[6:7], 0xa0000
	s_waitcnt vmcnt(0)
	v_pk_fma_f32 v[46:47], v[46:47], v[162:163], v[50:51]
	v_pk_fma_f32 v[44:45], v[44:45], v[164:165], v[48:49]
	global_store_dwordx4 v[54:55], v[44:47], off
	global_load_dwordx4 v[200:203], v[52:53], off offset:64
	global_load_dwordx4 v[204:207], v[52:53], off offset:512
	s_waitcnt vmcnt(1)
	v_pk_fma_f32 v[42:43], v[42:43], v[142:143], v[202:203]
	v_pk_fma_f32 v[40:41], v[40:41], v[160:161], v[200:201]
	global_store_dwordx4 v[52:53], v[40:43], off offset:64
	s_waitcnt vmcnt(1)
	v_pk_fma_f32 v[38:39], v[38:39], v[138:139], v[206:207]
	v_pk_fma_f32 v[36:37], v[36:37], v[140:141], v[204:205]
	global_store_dwordx4 v[52:53], v[36:39], off offset:512
	global_load_dwordx4 v[36:39], v[52:53], off offset:576
	s_waitcnt vmcnt(0)
	v_pk_fma_f32 v[32:33], v[32:33], v[134:135], v[36:37]
	v_lshl_add_u64 v[36:37], v[166:167], 0, s[6:7]
	s_mov_b32 s6, 0xa0000
	v_pk_fma_f32 v[34:35], v[34:35], v[136:137], v[38:39]
	v_add_co_u32_e32 v38, vcc, s6, v166
	global_store_dwordx4 v[52:53], v[32:35], off offset:576
	s_nop 0
	v_addc_co_u32_e32 v39, vcc, 0, v167, vcc
	global_load_dwordx4 v[32:35], v[38:39], off
	s_mov_b64 s[6:7], 0xb0000
	s_waitcnt vmcnt(0)
	v_pk_fma_f32 v[30:31], v[30:31], v[162:163], v[34:35]
	v_pk_fma_f32 v[28:29], v[28:29], v[164:165], v[32:33]
	global_store_dwordx4 v[38:39], v[28:31], off
	global_load_dwordx4 v[200:203], v[36:37], off offset:64
	global_load_dwordx4 v[204:207], v[36:37], off offset:512
	global_load_dwordx4 v[208:211], v[36:37], off offset:576
	s_waitcnt vmcnt(2)
	v_pk_fma_f32 v[26:27], v[26:27], v[142:143], v[202:203]
	v_pk_fma_f32 v[24:25], v[24:25], v[160:161], v[200:201]
	global_store_dwordx4 v[36:37], v[24:27], off offset:64
	s_waitcnt vmcnt(2)
	v_pk_fma_f32 v[22:23], v[22:23], v[138:139], v[206:207]
	v_pk_fma_f32 v[20:21], v[20:21], v[140:141], v[204:205]
	global_store_dwordx4 v[36:37], v[20:23], off offset:512
	s_waitcnt vmcnt(2)
	v_pk_fma_f32 v[18:19], v[18:19], v[136:137], v[210:211]
	v_pk_fma_f32 v[16:17], v[16:17], v[134:135], v[208:209]
	global_store_dwordx4 v[36:37], v[16:19], off offset:576
	s_nop 1
	v_lshl_add_u64 v[16:17], v[166:167], 0, s[6:7]
	s_mov_b32 s6, 0xb0000
	v_add_co_u32_e32 v22, vcc, s6, v166
	s_mov_b64 s[6:7], s[42:43]
	s_nop 0
	v_addc_co_u32_e32 v23, vcc, 0, v167, vcc
	global_load_dwordx4 v[18:21], v[22:23], off
	s_and_b64 vcc, exec, s[38:39]
	s_waitcnt vmcnt(0)
	v_pk_fma_f32 v[14:15], v[14:15], v[162:163], v[20:21]
	v_pk_fma_f32 v[12:13], v[12:13], v[164:165], v[18:19]
	global_store_dwordx4 v[22:23], v[12:15], off
	global_load_dwordx4 v[200:203], v[16:17], off offset:64
	global_load_dwordx4 v[204:207], v[16:17], off offset:512
	global_load_dwordx4 v[208:211], v[16:17], off offset:576
	s_waitcnt vmcnt(2)
	v_pk_fma_f32 v[10:11], v[10:11], v[142:143], v[202:203]
	v_pk_fma_f32 v[8:9], v[8:9], v[160:161], v[200:201]
	global_store_dwordx4 v[16:17], v[8:11], off offset:64
	s_waitcnt vmcnt(2)
	v_pk_fma_f32 v[6:7], v[6:7], v[138:139], v[206:207]
	v_pk_fma_f32 v[4:5], v[4:5], v[140:141], v[204:205]
	global_store_dwordx4 v[16:17], v[4:7], off offset:512
	s_waitcnt vmcnt(2)
	v_pk_fma_f32 v[2:3], v[2:3], v[136:137], v[210:211]
	v_pk_fma_f32 v[0:1], v[0:1], v[134:135], v[208:209]
	global_store_dwordx4 v[16:17], v[0:3], off offset:576
	s_cbranch_vccnz .LBB0_1133
